# DA phase: one static priority raise for waves 0-3 (the QK->softmax->PV role of the stagger), reset at the end of the phase; on top of the rope-table reuse
# speedup vs baseline: 1.0058x; 1.0058x over previous
.LBB0_276:
	s_cmp_gt_i32 s88, 3
	s_cselect_b64 s[0:1], -1, 0
	s_cmp_lt_i32 s89, 4
	s_cselect_b64 s[2:3], -1, 0
	s_or_b64 s[0:1], s[0:1], s[2:3]
	s_and_b64 vcc, exec, s[0:1]
	s_cbranch_vccnz .LBB0_356
	s_cmpk_gt_i32 s10, 0x8ff
	s_cbranch_scc1 .LBB0_304
	v_readlane_b32 s98, v239, 43
	s_nop 3
	s_cmpk_lt_u32 s98, 0x100
	s_cbranch_scc0 .Lprio_skip_da
	s_setprio 1
.Lprio_skip_da:
	v_readlane_b32 s1, v239, 43
	v_mbcnt_lo_u32_b32 v0, -1, 0
	s_and_b32 s0, s1, 0xffffffc0
	s_bfe_u32 s11, s1, 0x10006
	v_mbcnt_hi_u32_b32 v166, -1, v0
	s_lshl_b32 s8, s11, 3
	v_lshrrev_b32_e32 v168, 5, v166
	v_add_u32_e32 v0, s0, v166
	v_ashrrev_i32_e32 v148, 4, v0
	v_lshlrev_b32_e32 v2, 3, v166
	v_ashrrev_i32_e32 v152, 3, v0
	v_add_u32_e32 v0, s8, v168
	s_lshr_b32 s6, s1, 7
	v_and_b32_e32 v172, 8, v2
	v_bitop3_b32 v2, v0, v166, 15 bitop3:0x78
	s_lshl_b32 s12, s6, 5
	s_and_b32 s4, 64, s1
	v_lshlrev_b32_e32 v174, 4, v2
	v_add_u32_e32 v2, 2, v0
	s_cmp_eq_u32 s11, 0
	v_bitop3_b32 v2, v2, v166, 15 bitop3:0x78
	s_cselect_b64 s[2:3], -1, 0
	s_cmp_lg_u32 s4, 0
	v_readlane_b32 s36, v239, 32
	v_and_b32_e32 v167, 31, v166
	v_xor_b32_e32 v4, v148, v166
	v_lshlrev_b32_e32 v175, 4, v2
	v_add_u32_e32 v2, 4, v0
	v_add_u32_e32 v0, 6, v0
	s_cselect_b64 s[4:5], -1, 0
	s_lshl_b32 s13, s6, 14
	s_add_i32 s22, s12, 0x100
	s_lshl_b32 s23, s11, 6
	v_readlane_b32 s40, v239, 36
	s_movk_i32 s9, 0xff90
	v_lshlrev_b32_e32 v4, 4, v4
	v_lshlrev_b32_e32 v173, 8, v167
	v_bitop3_b32 v2, v2, v166, 15 bitop3:0x78
	v_bitop3_b32 v0, v0, v166, 15 bitop3:0x78
	v_readlane_b32 s37, v239, 33
	v_readlane_b32 s38, v239, 34
	v_readlane_b32 s39, v239, 35
	v_readlane_b32 s41, v239, 37
	v_readlane_b32 s42, v239, 38
	v_readlane_b32 s43, v239, 39
	s_add_u32 s30, s40, 0x30000
	v_lshlrev_b32_e32 v146, 4, v168
	v_lshlrev_b32_e32 v3, 4, v166
	s_waitcnt lgkmcnt(1)
	v_and_b32_e32 v5, 7, v166
	v_lshlrev_b32_e32 v170, 8, v148
	v_and_b32_e32 v171, 0xf0, v4
	v_lshlrev_b32_e32 v176, 4, v2
	v_lshlrev_b32_e32 v177, 4, v0
	v_mad_i32_i24 v0, v167, s9, v173
	s_mov_b32 s1, 0
	s_addc_u32 s31, s41, 0
	s_lshl_b32 s33, s10, 8
	s_lshl_b32 s34, s14, 8
	v_mov_b32_e32 v1, 0
	s_movk_i32 s35, 0x1200
	s_mov_b32 s36, 0x10000
	s_movk_i32 s37, 0x90
	s_mov_b32 s38, 0x48000
	s_mov_b32 s39, 0x20000
	s_mov_b32 s40, 0x30000
	s_mov_b32 s41, 0xff800000
	s_mov_b32 s42, 0x40000
	s_mov_b32 s43, 0x50000
	v_mov_b32_e32 v145, 0xbfb8aa3b
	s_mov_b32 s44, 0x60000
	s_mov_b32 s45, 0x70000
	v_mov_b32_e32 v157, 0x358637bd
	s_mov_b32 s46, 0x800000
	s_mov_b32 s47, 0xffff0000
	s_mov_b64 s[6:7], 0x20000
	v_mov_b32_e32 v169, 0x900
	v_ashrrev_i32_e32 v149, 31, v148
	v_and_b32_e32 v150, 0xf0, v3
	v_ashrrev_i32_e32 v153, 31, v152
	v_lshlrev_b32_e32 v154, 4, v5
	v_and_b32_e32 v156, 0x60, v3
	v_or_b32_e32 v178, v170, v171
	v_add_u32_e32 v179, v173, v174
	v_add_u32_e32 v180, v173, v175
	v_add_u32_e32 v181, v173, v176
	v_add_u32_e32 v182, v173, v177
	v_mov_b32_e32 v183, 0xff800000
	v_add_u32_e32 v184, v0, v146
	v_mov_b32_e32 v185, 0x480000
	s_mov_b32 s48, s10
	s_branch .LBB0_281
